# plus: last arriver skips generation bump in local seams; residual-phase first-tile DMA issued before the residual-row wait ladder; row-scale table wait counted
# speedup vs baseline: 1.0104x; 1.0019x over previous
;     __device__ __forceinline__ void pre(int tid) const { if (tid < BM) rsl_w[tid] = 1.0f / sqrtf(((rs_raw[0] + rs_raw[1]) + (rs_raw[2] + rs_raw[3])) * (1.0f / 1024.0f) + 1e-6f); }
;     __device__ __forceinline__ void pre(int tid) const { if (tid < BM) rsl_w[tid] = 1.0f / sqrtf(((rs_raw[0] + rs_raw[1]) + (rs_raw[2] + rs_raw[3])) * (1.0f / 1024.0f) + 1e-6f); }
; #define PG8_STAGE(bufoff, gbase, voff) do { _Pragma("unroll") for (int _i = 0; _i < 2; ++_i) \
;         __builtin_amdgcn_global_load_lds((const unsigned*)((const char*)(gbase) + (voff)[_i]), (PG8_LAS unsigned*)(lds + (bufoff) + ldsw + _i * 8192), 16, 0, 0); } while (0)
; #define PG8_WAIT_V(n) asm volatile("s_waitcnt vmcnt(" #n ")" ::: "memory")
; #define PG8_BAR __builtin_amdgcn_s_barrier()
; template <class Epi, class Sched, bool ALIGN_EPI = false, bool SP2 = false>
; __device__ __forceinline__ void gemm_phase(PG8_LAS unsigned char* lds, const Gemm g, const Sched& S, const Epi& E, const int tid_in) {
;     ...
;         PG8_STAGE(PG8_SB(0, 0), cB, voffB); PG8_STAGE(PG8_SB(0, 1), cB + hstepB, voffB); PG8_STAGE(PG8_SA(0, 0), cA, voffA); PG8_STAGE(PG8_SA(0, 1), cA + hstepA, voffA);
;         if (wr == 1) PG8_BAR;
;         PG8_WAIT_V(2); PG8_BAR;
;         PG8_STAGE(PG8_SB(1, 0), cB + kstep, voffB); PG8_STAGE(PG8_SA(1, 0), cA + kstep, voffA); PG8_STAGE(PG8_SB(1, 1), cB + hstepB + kstep, voffB);
;         PG8_WAIT_V(6); PG8_BAR;
;     } else {
;         PG8_STAGE(PG8_SB(0, 0), cB, voffB); PG8_STAGE(PG8_SA(0, 0), cA, voffA); PG8_STAGE(PG8_SB(0, 1), cB + hstepB, voffB); PG8_STAGE(PG8_SA(0, 1), cA + hstepA, voffA);
;         if (wr == 1) PG8_BAR;
;         PG8_WAIT_V(4); PG8_BAR;
;         PG8_STAGE(PG8_SB(1, 0), cB + kstep, voffB); PG8_STAGE(PG8_SA(1, 0), cA + kstep, voffA); PG8_STAGE(PG8_SB(1, 1), cB + hstepB + kstep, voffB);
;         PG8_WAIT_V(6); PG8_BAR;
;     }
;     if constexpr (Epi::HAS_PRE) E.pre(tid);
.LBB0_212:
	v_mov_b32_e32 v145, v115
	v_mov_b32_e32 v149, v115
	v_lshl_add_u64 v[12:13], s[20:21], 0, v[144:145]
	v_mov_b32_e32 v113, v115
	v_lshl_add_u64 v[14:15], s[20:21], 0, v[148:149]
	s_add_i32 m0, s28, 0x18000
	v_lshl_add_u64 v[12:13], v[12:13], 0, s[10:11]
	v_mov_b32_e32 v147, v115
	v_lshl_add_u64 v[18:19], s[0:1], 0, v[112:113]
	s_waitcnt vmcnt(2)
	s_barrier
	global_load_lds_dwordx4 v[12:13], off
	v_lshl_add_u64 v[12:13], v[14:15], 0, s[10:11]
	s_add_i32 m0, s28, 0x1a000
	s_add_i32 s64, s28, 0x8000
	s_add_i32 s65, s28, 0xa000
	v_lshl_add_u64 v[20:21], s[0:1], 0, v[146:147]
	global_load_lds_dwordx4 v[12:13], off
	v_lshl_add_u64 v[12:13], v[18:19], 0, s[10:11]
	s_mov_b32 m0, s64
	s_add_u32 s14, s20, 0x40080
	global_load_lds_dwordx4 v[12:13], off
	v_lshl_add_u64 v[12:13], v[20:21], 0, s[10:11]
	s_mov_b32 m0, s65
	s_addc_u32 s15, s21, 0
	global_load_lds_dwordx4 v[12:13], off
	s_add_i32 m0, s28, 0x1c000
	v_lshl_add_u64 v[12:13], s[14:15], 0, v[144:145]
	global_load_lds_dwordx4 v[12:13], off
	v_lshl_add_u64 v[12:13], s[14:15], 0, v[148:149]
	s_add_i32 m0, s28, 0x1e000
	s_nop 0
	global_load_lds_dwordx4 v[12:13], off
	s_waitcnt vmcnt(6)
	s_barrier
	s_and_saveexec_b64 s[14:15], s[4:5]
	s_cbranch_execz .LBB0_214
	s_waitcnt vmcnt(6)
	v_add_f32_e32 v0, v0, v1
	v_add_f32_e32 v1, v2, v3
	v_add_f32_e32 v0, v0, v1
	v_fmamk_f32 v0, v0, 0x3a800000, v228
	v_mul_f32_e32 v1, 0x4f800000, v0
	v_cmp_gt_f32_e32 vcc, s36, v0
	s_nop 1
	v_cndmask_b32_e32 v0, v0, v1, vcc
	v_sqrt_f32_e32 v1, v0
	s_nop 0
	v_add_u32_e32 v2, -1, v1
	v_fma_f32 v3, -v2, v1, v0
	v_cmp_ge_f32_e64 s[4:5], 0, v3
	v_add_u32_e32 v3, 1, v1
	s_nop 0
	v_cndmask_b32_e64 v2, v1, v2, s[4:5]
	v_fma_f32 v1, -v3, v1, v0
	v_cmp_lt_f32_e64 s[4:5], 0, v1
	s_nop 1
	v_cndmask_b32_e64 v1, v2, v3, s[4:5]
	v_mul_f32_e32 v2, 0x37800000, v1
	v_cndmask_b32_e32 v1, v1, v2, vcc
	v_cmp_class_f32_e32 vcc, v0, v229
	s_nop 1
	v_cndmask_b32_e32 v0, v1, v0, vcc
	v_div_scale_f32 v1, s[4:5], v0, v0, 1.0
	v_rcp_f32_e32 v2, v1
	s_nop 0
	v_fma_f32 v3, -v1, v2, 1.0
	v_fmac_f32_e32 v2, v3, v2
	v_div_scale_f32 v3, vcc, 1.0, v0, 1.0
	v_mul_f32_e32 v11, v3, v2
	v_fma_f32 v12, -v1, v11, v3
	v_fmac_f32_e32 v11, v12, v2
	v_fma_f32 v1, -v1, v11, v3
	v_div_fmas_f32 v1, v1, v2, v11
	v_div_fixup_f32 v0, v1, v0, 1.0
	v_lshl_add_u32 v1, v4, 2, 0
	v_add_u32_e32 v1, 0x22200, v1
	ds_write_b32 v1, v0

; __device__ __forceinline__ void xcd_barrier(const XcdBarrier& b, const bool local_only = false) {
;     ...
;     }
;     __syncthreads();
; }
.Lxb_ld_exit_2:
.LBB0_325:
	s_or_b64 exec, exec, s[0:1]
	s_waitcnt lgkmcnt(0)
	s_barrier

; #define PG8_STAGE(bufoff, gbase, voff) do { _Pragma("unroll") for (int _i = 0; _i < 2; ++_i) \
;         __builtin_amdgcn_global_load_lds((const unsigned*)((const char*)(gbase) + (voff)[_i]), (PG8_LAS unsigned*)(lds + (bufoff) + ldsw + _i * 8192), 16, 0, 0); } while (0)
; #define PG8_WAIT_V(n) asm volatile("s_waitcnt vmcnt(" #n ")" ::: "memory")
; #define PG8_BAR __builtin_amdgcn_s_barrier()
;     __device__ __forceinline__ void init(f32x4 (&acc)[2][2][4][2], const Unit& u, int wr, int wc, int fr, int fq) const {
;         const int col0 = u.pn * BM + wc * 32 + 8 * fq;
; #pragma unroll
;         for (int ai = 0; ai < 2; ++ai)
; #pragma unroll
;             for (int m = 0; m < 4; ++m) { const size_t off = (size_t)(u.pm * BM + ai * HALF + wr * 64 + m * 16 + fr) * ldc + col0;
; #pragma unroll
;                 for (int bj = 0; bj < 2; ++bj) { const size_t p = off + bj * HALF;
;                     if (base32) { acc[ai][bj][m][0] = *(const f32x4*)(base32 + p); acc[ai][bj][m][1] = *(const f32x4*)(base32 + p + 4); }
;                     else { const u32x4 r = *(const u32x4*)(xn + p); acc[ai][bj][m][0] = (f32x4){__uint_as_float(r.x << 16), __uint_as_float(r.x & 0xffff0000u), __uint_as_float(r.y << 16), __uint_as_float(r.y & 0xffff0000u)};
;                         acc[ai][bj][m][1] = (f32x4){__uint_as_float(r.z << 16), __uint_as_float(r.z & 0xffff0000u), __uint_as_float(r.w << 16), __uint_as_float(r.w & 0xffff0000u)}; } } }
; template <class Epi, class Sched, bool ALIGN_EPI = false, bool SP2 = false>
; __device__ __forceinline__ void gemm_phase(PG8_LAS unsigned char* lds, const Gemm g, const Sched& S, const Epi& E, const int tid_in) {
;     ...
;     const char* cA = (const char*)g.A + (size_t)cur.pm * tstepA + (size_t)(cur.pm >> 3) * g.abx; const char* cB = (const char*)g.Bt + (size_t)cur.pn * tstepB;
;     S.a_ready(cur);
;     if constexpr (SP2) {
;         PG8_STAGE(PG8_SB(0, 0), cB, voffB); PG8_STAGE(PG8_SB(0, 1), cB + hstepB, voffB); PG8_STAGE(PG8_SA(0, 0), cA, voffA); PG8_STAGE(PG8_SA(0, 1), cA + hstepA, voffA);
;         if (wr == 1) PG8_BAR;
;         PG8_WAIT_V(2); PG8_BAR;
;         PG8_STAGE(PG8_SB(1, 0), cB + kstep, voffB); PG8_STAGE(PG8_SA(1, 0), cA + kstep, voffA); PG8_STAGE(PG8_SB(1, 1), cB + hstepB + kstep, voffB);
;         PG8_WAIT_V(6); PG8_BAR;
.LBB0_493:
	s_cmp_le_i32 s92, s48
	s_cselect_b64 s[0:1], -1, 0
	s_cmp_lt_i32 s48, s93
	s_cselect_b64 s[4:5], -1, 0
	s_and_b64 s[0:1], s[0:1], s[4:5]
	s_andn2_b64 vcc, exec, s[0:1]
	s_mov_b64 s[0:1], 0
	s_cbranch_vccnz .LBB0_545
	s_mov_b32 s4, -1
	s_load_dwordx2 s[18:19], s[12:13], 0x88
	s_waitcnt vmcnt(0)
	v_mbcnt_lo_u32_b32 v0, s4, 0
	v_mbcnt_hi_u32_b32 v1, s4, v0
	v_readlane_b32 s4, v254, 14
	v_add_u32_e32 v0, s97, v1
	v_readlane_b32 s5, v254, 15
	s_andn2_b64 vcc, exec, s[4:5]
	v_readfirstlane_b32 s6, v0
	s_cbranch_vccnz .LBB0_534
	v_readlane_b32 s4, v255, 5
	s_lshl_b32 s4, s4, 20
	s_and_b32 s4, s4, 0x200000
	v_readlane_b32 s5, v255, 6
	s_waitcnt lgkmcnt(0)
	s_add_u32 s4, s18, s4
	s_addc_u32 s5, s19, 0
	s_add_u32 s48, s4, 0x3000000
	v_bfe_u32 v147, v1, 4, 2
	v_and_b32_e32 v146, 15, v1
	v_lshlrev_b32_e32 v1, 4, v0
	s_addc_u32 s58, s5, 0
	v_add_u32_e32 v2, 0x2000, v1
	s_add_u32 s20, s18, 0x7400000
	v_ashrrev_i32_e32 v3, 31, v2
	s_addc_u32 s21, s19, 0
	s_ashr_i32 s5, s6, 6
	v_lshrrev_b32_e32 v3, 22, v3
	s_and_b32 s8, s5, 3
	v_add_u32_e32 v3, v2, v3
	s_lshl_b32 s59, s5, 10
	s_lshl_b32 s9, s8, 5
	v_ashrrev_i32_e32 v149, 10, v3
	v_readlane_b32 s5, v254, 32
	s_ashr_i32 s4, s6, 8
	v_lshlrev_b32_e32 v148, 3, v147
	v_mul_i32_i24_e32 v3, 0x400, v149
	s_or_b32 s5, s5, s9
	v_lshl_or_b32 v144, s4, 6, v146
	v_sub_u32_e32 v10, v2, v3
	v_or_b32_e32 v2, s5, v148
	v_readlane_b32 s5, v254, 36
	v_lshrrev_b32_e32 v11, 4, v10
	v_ashrrev_i32_e32 v3, 31, v2
	v_add_u32_e32 v8, s5, v144
	v_ashrrev_i32_e32 v9, 31, v8
	v_lshlrev_b64 v[4:5], 11, v[8:9]
	v_bitop3_b32 v9, v11, v10, 32 bitop3:0x6c
	v_ashrrev_i32_e32 v10, 31, v9
	v_lshrrev_b32_e32 v10, 26, v10
	v_add_u32_e32 v10, v9, v10
	v_lshlrev_b32_e32 v11, 3, v149
	v_ashrrev_i32_e32 v150, 6, v10
	v_and_b32_e32 v11, -16, v11
	v_add_u32_e32 v11, v150, v11
	v_and_b32_e32 v12, 3, v150
	s_mov_b32 s5, 0x1fffe0
	v_lshl_add_u64 v[4:5], s[20:21], 0, v[4:5]
	v_lshlrev_b64 v[34:35], 1, v[2:3]
	v_and_or_b32 v16, v11, s5, v12
	v_lshrrev_b32_e32 v12, 2, v11
	v_and_b32_e32 v10, 0xc0, v10
	v_lshl_add_u64 v[2:3], v[4:5], 0, v[34:35]
	v_and_b32_e32 v17, 4, v12
	v_lshlrev_b32_e32 v12, 1, v11
	v_sub_u32_e32 v9, v9, v10
	global_load_dwordx4 v[4:7], v[2:3], off
	v_and_b32_e32 v18, 24, v12
	global_load_dwordx4 v[12:15], v[2:3], off offset:256
	v_lshlrev_b32_e32 v3, 5, v149
	v_ashrrev_i16_sdwa v9, v233, sext(v9) dst_sel:DWORD dst_unused:UNUSED_PAD src0_sel:DWORD src1_sel:BYTE_0
	v_and_b32_e32 v3, 32, v3
	v_bfe_i32 v151, v9, 0, 16
	v_or3_b32 v2, v16, v17, v18
	v_add_lshl_u32 v9, v3, v151, 1
	v_lshl_add_u32 v112, v2, 11, v9
	v_lshl_add_u32 v132, v11, 11, v9
	v_bfe_i32 v9, v0, 27, 1
	v_lshrrev_b32_e32 v9, 22, v9
	v_add_u32_e32 v9, v1, v9
	v_and_b32_e32 v9, 0xfffffc00, v9
	v_add_u32_e32 v2, 16, v8
	v_sub_u32_e32 v1, v1, v9
	v_ashrrev_i32_e32 v3, 31, v2
	v_lshrrev_b32_e32 v9, 4, v1
	v_lshlrev_b64 v[2:3], 11, v[2:3]
	v_bitop3_b32 v9, v9, v1, 32 bitop3:0x6c
	v_lshl_add_u64 v[2:3], s[20:21], 0, v[2:3]
	v_ashrrev_i32_e32 v1, 31, v9
	v_lshl_add_u64 v[2:3], v[2:3], 0, v[34:35]
	v_lshrrev_b32_e32 v1, 26, v1
	global_load_dwordx4 v[20:23], v[2:3], off
	global_load_dwordx4 v[28:31], v[2:3], off offset:256
	v_add_u32_e32 v2, v9, v1
	v_ashrrev_i32_e32 v1, 31, v0
	v_lshrrev_b32_e32 v1, 26, v1
	v_add_u32_e32 v0, v0, v1
	v_ashrrev_i32_e32 v153, 6, v0
	v_add_u32_e32 v0, 32, v8
	v_ashrrev_i32_e32 v1, 31, v0
	v_lshlrev_b64 v[0:1], 11, v[0:1]
	v_ashrrev_i32_e32 v152, 6, v2
	v_lshl_add_u64 v[0:1], s[20:21], 0, v[0:1]
	v_and_b32_e32 v2, 0xc0, v2
	v_lshl_add_u64 v[0:1], v[0:1], 0, v[34:35]
	v_sub_u32_e32 v2, v9, v2
	global_load_dwordx4 v[36:39], v[0:1], off
	global_load_dwordx4 v[44:47], v[0:1], off offset:256
	v_ashrrev_i16_sdwa v0, v233, sext(v2) dst_sel:DWORD dst_unused:UNUSED_PAD src0_sel:DWORD src1_sel:BYTE_0
	v_bfe_i32 v154, v0, 0, 16
	v_add_u32_e32 v0, 48, v8
	v_lshlrev_b32_e32 v3, 3, v153
	v_ashrrev_i32_e32 v1, 31, v0
	v_and_b32_e32 v3, -16, v3
	v_lshlrev_b64 v[0:1], 11, v[0:1]
	v_add_u32_e32 v3, v152, v3
	v_and_b32_e32 v10, 3, v152
	v_lshl_add_u64 v[0:1], s[20:21], 0, v[0:1]
	v_and_or_b32 v10, v3, s5, v10
	v_lshl_add_u64 v[8:9], v[0:1], 0, v[34:35]
	v_readlane_b32 s5, v254, 33
	global_load_dwordx4 v[52:55], v[8:9], off
	global_load_dwordx4 v[60:63], v[8:9], off offset:256
	v_add_u32_e32 v8, s5, v144
	v_ashrrev_i32_e32 v9, 31, v8
	v_lshrrev_b32_e32 v11, 2, v3
	v_lshlrev_b32_e32 v16, 1, v3
	v_lshlrev_b64 v[8:9], 11, v[8:9]
	v_and_b32_e32 v11, 4, v11
	v_and_b32_e32 v16, 24, v16
	v_lshl_add_u64 v[8:9], s[20:21], 0, v[8:9]
	v_or3_b32 v10, v10, v11, v16
	v_lshl_add_u64 v[16:17], v[8:9], 0, v[34:35]
	v_readlane_b32 s5, v254, 34
	global_load_dwordx4 v[68:71], v[16:17], off
	global_load_dwordx4 v[76:79], v[16:17], off offset:256
	v_add_u32_e32 v16, s5, v144
	v_readlane_b32 s5, v254, 35
	v_ashrrev_i32_e32 v17, 31, v16
	v_lshlrev_b64 v[16:17], 11, v[16:17]
	v_add_u32_e32 v26, s5, v144
	v_readlane_b32 s5, v254, 37
	v_ashrrev_i32_e32 v27, 31, v26
	v_lshlrev_b64 v[26:27], 11, v[26:27]
	v_add_u32_e32 v40, s5, v144
	v_ashrrev_i32_e32 v41, 31, v40
	v_lshlrev_b64 v[40:41], 11, v[40:41]
	v_lshl_add_u64 v[16:17], s[20:21], 0, v[16:17]
	v_lshl_add_u64 v[26:27], s[20:21], 0, v[26:27]
	v_lshl_add_u64 v[40:41], s[20:21], 0, v[40:41]
	v_lshl_add_u64 v[24:25], v[16:17], 0, v[34:35]
	v_lshl_add_u64 v[32:33], v[26:27], 0, v[34:35]
	v_lshl_add_u64 v[42:43], v[40:41], 0, v[34:35]
	global_load_dwordx4 v[84:87], v[24:25], off
	global_load_dwordx4 v[92:95], v[24:25], off offset:256
	global_load_dwordx4 v[100:103], v[32:33], off
	global_load_dwordx4 v[108:111], v[32:33], off offset:256
	global_load_dwordx4 v[120:123], v[42:43], off
	global_load_dwordx4 v[128:131], v[42:43], off offset:256
	v_lshlrev_b32_e32 v11, 5, v153
	v_readlane_b32 s14, v254, 42
	v_and_b32_e32 v11, 32, v11
	v_readlane_b32 s15, v254, 43
	s_add_u32 s54, s48, s14
	v_add_lshl_u32 v2, v11, v154, 1
	s_addc_u32 s55, s58, s15
	s_add_i32 s60, s59, 0
	v_lshl_add_u32 v114, v10, 11, v2
	v_lshl_add_u32 v134, v3, 11, v2
	s_add_i32 m0, s60, 0x10000
	s_nop 0
	global_load_lds_dwordx4 v114, s[54:55]
	s_add_i32 m0, s60, 0x12000
	v_readlane_b32 s14, v254, 38
	v_readlane_b32 s15, v254, 39
	s_add_u32 s5, s64, s14
	s_addc_u32 s7, s65, s15
	s_add_u32 s14, s54, 0x40000
	global_load_lds_dwordx4 v112, s[54:55]
	s_addc_u32 s15, s55, 0
	s_add_i32 m0, s60, 0x14000
	v_mov_b32_e32 v113, v115
	global_load_lds_dwordx4 v114, s[14:15]
	s_add_i32 m0, s60, 0x16000
	v_mov_b32_e32 v135, v115
	global_load_lds_dwordx4 v112, s[14:15]
	v_readlane_b32 s14, v254, 41
	s_add_u32 s50, s5, s14
	v_readlane_b32 s5, v254, 40
	s_addc_u32 s51, s7, s5
	s_add_i32 s61, s60, 0x2000
	s_mov_b32 m0, s60
	s_add_u32 s14, s50, 0x40000
	global_load_lds_dwordx4 v134, s[50:51]
	s_mov_b32 m0, s61
	s_addc_u32 s15, s51, 0
	s_add_i32 s62, s60, 0x4000
	global_load_lds_dwordx4 v132, s[50:51]
	s_mov_b32 m0, s62
	s_add_i32 s63, s60, 0x6000
	global_load_lds_dwordx4 v134, s[14:15]
	s_mov_b32 m0, s63
	v_mov_b32_e32 v133, v115
	global_load_lds_dwordx4 v132, s[14:15]
	s_waitcnt vmcnt(23)
; #define PG8_STAGE(bufoff, gbase, voff) do { _Pragma("unroll") for (int _i = 0; _i < 2; ++_i) \
;         __builtin_amdgcn_global_load_lds((const unsigned*)((const char*)(gbase) + (voff)[_i]), (PG8_LAS unsigned*)(lds + (bufoff) + ldsw + _i * 8192), 16, 0, 0); } while (0)
; #define PG8_BAR __builtin_amdgcn_s_barrier()
;     __device__ __forceinline__ void init(f32x4 (&acc)[2][2][4][2], const Unit& u, int wr, int wc, int fr, int fq) const {
;     ...
;                 for (int bj = 0; bj < 2; ++bj) { const size_t p = off + bj * HALF;
;                     if (base32) { acc[ai][bj][m][0] = *(const f32x4*)(base32 + p); acc[ai][bj][m][1] = *(const f32x4*)(base32 + p + 4); }
;                     else { const u32x4 r = *(const u32x4*)(xn + p); acc[ai][bj][m][0] = (f32x4){__uint_as_float(r.x << 16), __uint_as_float(r.x & 0xffff0000u), __uint_as_float(r.y << 16), __uint_as_float(r.y & 0xffff0000u)};
;                         acc[ai][bj][m][1] = (f32x4){__uint_as_float(r.z << 16), __uint_as_float(r.z & 0xffff0000u), __uint_as_float(r.w << 16), __uint_as_float(r.w & 0xffff0000u)}; } } }
; #pragma unroll
;         for (int ai = 0; ai < 2; ++ai)
; #pragma unroll
;             for (int bj = 0; bj < 2; ++bj)
; #pragma unroll
;                 for (int m = 0; m < 4; ++m) asm volatile("" : "+v"(acc[ai][bj][m][0]), "+v"(acc[ai][bj][m][1]));
; template <class Epi, class Sched, bool ALIGN_EPI = false, bool SP2 = false>
; __device__ __forceinline__ void gemm_phase(PG8_LAS unsigned char* lds, const Gemm g, const Sched& S, const Epi& E, const int tid_in) {
;     ...
;         PG8_STAGE(PG8_SB(0, 0), cB, voffB); PG8_STAGE(PG8_SB(0, 1), cB + hstepB, voffB); PG8_STAGE(PG8_SA(0, 0), cA, voffA); PG8_STAGE(PG8_SA(0, 1), cA + hstepA, voffA);
;         if (wr == 1) PG8_BAR;
	v_lshlrev_b32_e32 v0, 16, v4
	v_and_b32_e32 v1, 0xffff0000, v4
	v_lshlrev_b32_e32 v2, 16, v5
	v_and_b32_e32 v3, 0xffff0000, v5
	v_lshlrev_b32_e32 v4, 16, v6
	v_and_b32_e32 v5, 0xffff0000, v6
	v_lshlrev_b32_e32 v6, 16, v7
	v_and_b32_e32 v7, 0xffff0000, v7
	s_waitcnt vmcnt(22)
	v_lshlrev_b32_e32 v8, 16, v12
	v_and_b32_e32 v9, 0xffff0000, v12
	v_lshlrev_b32_e32 v10, 16, v13
	v_and_b32_e32 v11, 0xffff0000, v13
	v_lshlrev_b32_e32 v12, 16, v14
	v_and_b32_e32 v13, 0xffff0000, v14
	v_lshlrev_b32_e32 v14, 16, v15
	v_and_b32_e32 v15, 0xffff0000, v15
	s_waitcnt vmcnt(21)
	v_lshlrev_b32_e32 v16, 16, v20
	v_and_b32_e32 v17, 0xffff0000, v20
	v_lshlrev_b32_e32 v18, 16, v21
	v_and_b32_e32 v19, 0xffff0000, v21
	v_lshlrev_b32_e32 v20, 16, v22
	v_and_b32_e32 v21, 0xffff0000, v22
	v_lshlrev_b32_e32 v22, 16, v23
	v_and_b32_e32 v23, 0xffff0000, v23
	s_waitcnt vmcnt(20)
	v_lshlrev_b32_e32 v24, 16, v28
	v_and_b32_e32 v25, 0xffff0000, v28
	v_lshlrev_b32_e32 v26, 16, v29
	v_and_b32_e32 v27, 0xffff0000, v29
	v_lshlrev_b32_e32 v28, 16, v30
	v_and_b32_e32 v29, 0xffff0000, v30
	v_lshlrev_b32_e32 v30, 16, v31
	v_and_b32_e32 v31, 0xffff0000, v31
	s_waitcnt vmcnt(19)
	v_lshlrev_b32_e32 v32, 16, v36
	v_and_b32_e32 v33, 0xffff0000, v36
	v_lshlrev_b32_e32 v34, 16, v37
	v_and_b32_e32 v35, 0xffff0000, v37
	v_lshlrev_b32_e32 v36, 16, v38
	v_and_b32_e32 v37, 0xffff0000, v38
	v_lshlrev_b32_e32 v38, 16, v39
	v_and_b32_e32 v39, 0xffff0000, v39
	s_waitcnt vmcnt(18)
	v_lshlrev_b32_e32 v40, 16, v44
	v_and_b32_e32 v41, 0xffff0000, v44
	v_lshlrev_b32_e32 v42, 16, v45
	v_and_b32_e32 v43, 0xffff0000, v45
	v_lshlrev_b32_e32 v44, 16, v46
	v_and_b32_e32 v45, 0xffff0000, v46
	v_lshlrev_b32_e32 v46, 16, v47
	v_and_b32_e32 v47, 0xffff0000, v47
	s_waitcnt vmcnt(17)
	v_lshlrev_b32_e32 v48, 16, v52
	v_and_b32_e32 v49, 0xffff0000, v52
	v_lshlrev_b32_e32 v50, 16, v53
	v_and_b32_e32 v51, 0xffff0000, v53
	v_lshlrev_b32_e32 v52, 16, v54
	v_and_b32_e32 v53, 0xffff0000, v54
	v_lshlrev_b32_e32 v54, 16, v55
	v_and_b32_e32 v55, 0xffff0000, v55
	s_waitcnt vmcnt(16)
	v_lshlrev_b32_e32 v56, 16, v60
	v_and_b32_e32 v57, 0xffff0000, v60
	v_lshlrev_b32_e32 v58, 16, v61
	v_and_b32_e32 v59, 0xffff0000, v61
	v_lshlrev_b32_e32 v60, 16, v62
	v_and_b32_e32 v61, 0xffff0000, v62
	v_lshlrev_b32_e32 v62, 16, v63
	v_and_b32_e32 v63, 0xffff0000, v63
	s_waitcnt vmcnt(15)
	v_lshlrev_b32_e32 v64, 16, v68
	v_and_b32_e32 v65, 0xffff0000, v68
	v_lshlrev_b32_e32 v66, 16, v69
	v_and_b32_e32 v67, 0xffff0000, v69
	v_lshlrev_b32_e32 v68, 16, v70
	v_and_b32_e32 v69, 0xffff0000, v70
	v_lshlrev_b32_e32 v70, 16, v71
	v_and_b32_e32 v71, 0xffff0000, v71
	s_waitcnt vmcnt(14)
	v_lshlrev_b32_e32 v72, 16, v76
	v_and_b32_e32 v73, 0xffff0000, v76
	v_lshlrev_b32_e32 v74, 16, v77
	v_and_b32_e32 v75, 0xffff0000, v77
	v_lshlrev_b32_e32 v76, 16, v78
	v_and_b32_e32 v77, 0xffff0000, v78
	v_lshlrev_b32_e32 v78, 16, v79
	v_and_b32_e32 v79, 0xffff0000, v79
	s_waitcnt vmcnt(13)
	v_lshlrev_b32_e32 v80, 16, v84
	v_and_b32_e32 v81, 0xffff0000, v84
	v_lshlrev_b32_e32 v82, 16, v85
	v_and_b32_e32 v83, 0xffff0000, v85
	v_lshlrev_b32_e32 v84, 16, v86
	v_and_b32_e32 v85, 0xffff0000, v86
	v_lshlrev_b32_e32 v86, 16, v87
	v_and_b32_e32 v87, 0xffff0000, v87
	s_waitcnt vmcnt(12)
	v_lshlrev_b32_e32 v88, 16, v92
	v_and_b32_e32 v89, 0xffff0000, v92
	v_lshlrev_b32_e32 v90, 16, v93
	v_and_b32_e32 v91, 0xffff0000, v93
	v_lshlrev_b32_e32 v92, 16, v94
	v_and_b32_e32 v93, 0xffff0000, v94
	v_lshlrev_b32_e32 v94, 16, v95
	v_and_b32_e32 v95, 0xffff0000, v95
	s_waitcnt vmcnt(11)
	v_lshlrev_b32_e32 v96, 16, v100
	v_and_b32_e32 v97, 0xffff0000, v100
	v_lshlrev_b32_e32 v98, 16, v101
	v_and_b32_e32 v99, 0xffff0000, v101
	v_lshlrev_b32_e32 v100, 16, v102
	v_and_b32_e32 v101, 0xffff0000, v102
	v_lshlrev_b32_e32 v102, 16, v103
	v_and_b32_e32 v103, 0xffff0000, v103
	s_waitcnt vmcnt(10)
	v_lshlrev_b32_e32 v104, 16, v108
	v_and_b32_e32 v105, 0xffff0000, v108
	v_lshlrev_b32_e32 v106, 16, v109
	v_and_b32_e32 v107, 0xffff0000, v109
	v_lshlrev_b32_e32 v108, 16, v110
	v_and_b32_e32 v109, 0xffff0000, v110
	v_lshlrev_b32_e32 v110, 16, v111
	v_and_b32_e32 v111, 0xffff0000, v111
	s_waitcnt vmcnt(9)
	v_lshlrev_b32_e32 v116, 16, v120
	v_and_b32_e32 v117, 0xffff0000, v120
	v_lshlrev_b32_e32 v118, 16, v121
	v_and_b32_e32 v119, 0xffff0000, v121
	v_lshlrev_b32_e32 v120, 16, v122
	v_and_b32_e32 v121, 0xffff0000, v122
	v_lshlrev_b32_e32 v122, 16, v123
	v_and_b32_e32 v123, 0xffff0000, v123
	s_waitcnt vmcnt(8)
	v_lshlrev_b32_e32 v124, 16, v128
	v_and_b32_e32 v125, 0xffff0000, v128
	v_lshlrev_b32_e32 v126, 16, v129
	v_and_b32_e32 v127, 0xffff0000, v129
	v_lshlrev_b32_e32 v128, 16, v130
	v_and_b32_e32 v129, 0xffff0000, v130
	v_lshlrev_b32_e32 v130, 16, v131
	v_and_b32_e32 v131, 0xffff0000, v131
	s_cmp_eq_u32 s4, 1
	v_lshl_add_u64 v[142:143], s[54:55], 0, v[114:115]
	v_lshl_add_u64 v[140:141], s[54:55], 0, v[112:113]
	v_lshl_add_u64 v[136:137], s[50:51], 0, v[134:135]
	s_cselect_b64 s[22:23], -1, 0
	s_cmp_lg_u32 s4, 1
	v_lshl_add_u64 v[138:139], s[50:51], 0, v[132:133]
	s_cbranch_scc1 .LBB0_497
	s_barrier

; __device__ __forceinline__ void xcd_barrier(const XcdBarrier& b, const bool local_only = false) {
;     ...
;     }
;     __syncthreads();
; }
.Lxb_ld_exit_6:
.LBB0_589:
	s_or_b64 exec, exec, s[8:9]
	s_waitcnt lgkmcnt(0)
	s_barrier
	s_mov_b64 s[4:5], -1

;     __device__ __forceinline__ void pre(int tid) const { if (tid < BM) rsl_w[tid] = 1.0f / sqrtf(((rs_raw[0] + rs_raw[1]) + (rs_raw[2] + rs_raw[3])) * (1.0f / 1024.0f) + 1e-6f); }
;     __device__ __forceinline__ void pre(int tid) const { if (tid < BM) rsl_w[tid] = 1.0f / sqrtf(((rs_raw[0] + rs_raw[1]) + (rs_raw[2] + rs_raw[3])) * (1.0f / 1024.0f) + 1e-6f); }
; #define PG8_STAGE(bufoff, gbase, voff) do { _Pragma("unroll") for (int _i = 0; _i < 2; ++_i) \
;         __builtin_amdgcn_global_load_lds((const unsigned*)((const char*)(gbase) + (voff)[_i]), (PG8_LAS unsigned*)(lds + (bufoff) + ldsw + _i * 8192), 16, 0, 0); } while (0)
; #define PG8_WAIT_V(n) asm volatile("s_waitcnt vmcnt(" #n ")" ::: "memory")
; #define PG8_BAR __builtin_amdgcn_s_barrier()
; template <class Epi, class Sched, bool ALIGN_EPI = false, bool SP2 = false>
; __device__ __forceinline__ void gemm_phase(PG8_LAS unsigned char* lds, const Gemm g, const Sched& S, const Epi& E, const int tid_in) {
;     ...
;         PG8_STAGE(PG8_SB(0, 0), cB, voffB); PG8_STAGE(PG8_SB(0, 1), cB + hstepB, voffB); PG8_STAGE(PG8_SA(0, 0), cA, voffA); PG8_STAGE(PG8_SA(0, 1), cA + hstepA, voffA);
;         if (wr == 1) PG8_BAR;
;         PG8_WAIT_V(2); PG8_BAR;
;         PG8_STAGE(PG8_SB(1, 0), cB + kstep, voffB); PG8_STAGE(PG8_SA(1, 0), cA + kstep, voffA); PG8_STAGE(PG8_SB(1, 1), cB + hstepB + kstep, voffB);
;         PG8_WAIT_V(6); PG8_BAR;
;     } else {
;         PG8_STAGE(PG8_SB(0, 0), cB, voffB); PG8_STAGE(PG8_SA(0, 0), cA, voffA); PG8_STAGE(PG8_SB(0, 1), cB + hstepB, voffB); PG8_STAGE(PG8_SA(0, 1), cA + hstepA, voffA);
;         if (wr == 1) PG8_BAR;
;         PG8_WAIT_V(4); PG8_BAR;
;         PG8_STAGE(PG8_SB(1, 0), cB + kstep, voffB); PG8_STAGE(PG8_SA(1, 0), cA + kstep, voffA); PG8_STAGE(PG8_SB(1, 1), cB + hstepB + kstep, voffB);
;         PG8_WAIT_V(6); PG8_BAR;
;     }
;     if constexpr (Epi::HAS_PRE) E.pre(tid);
.LBB0_601:
	v_mov_b32_e32 v159, v115
	v_lshl_add_u64 v[12:13], s[20:21], 0, v[114:115]
	v_mov_b32_e32 v113, v115
	v_lshl_add_u64 v[14:15], s[20:21], 0, v[158:159]
	s_add_i32 m0, s26, 0x18000
	v_lshl_add_u64 v[12:13], v[12:13], 0, s[10:11]
	v_mov_b32_e32 v157, v115
	v_lshl_add_u64 v[16:17], s[0:1], 0, v[112:113]
	s_waitcnt vmcnt(2)
	s_barrier
	global_load_lds_dwordx4 v[12:13], off
	v_lshl_add_u64 v[12:13], v[14:15], 0, s[10:11]
	s_add_i32 m0, s26, 0x1a000
	s_add_i32 s58, s26, 0x8000
	s_add_i32 s59, s26, 0xa000
	v_lshl_add_u64 v[18:19], s[0:1], 0, v[156:157]
	global_load_lds_dwordx4 v[12:13], off
	v_lshl_add_u64 v[12:13], v[16:17], 0, s[10:11]
	s_mov_b32 m0, s58
	s_add_u32 s14, s20, 0x40080
	global_load_lds_dwordx4 v[12:13], off
	v_lshl_add_u64 v[12:13], v[18:19], 0, s[10:11]
	s_mov_b32 m0, s59
	s_addc_u32 s15, s21, 0
	global_load_lds_dwordx4 v[12:13], off
	s_add_i32 m0, s26, 0x1c000
	v_lshl_add_u64 v[12:13], s[14:15], 0, v[114:115]
	global_load_lds_dwordx4 v[12:13], off
	v_lshl_add_u64 v[12:13], s[14:15], 0, v[158:159]
	s_add_i32 m0, s26, 0x1e000
	s_nop 0
	global_load_lds_dwordx4 v[12:13], off
	s_waitcnt vmcnt(6)
	s_barrier
	s_and_saveexec_b64 s[14:15], s[4:5]
	s_cbranch_execz .LBB0_603
	s_waitcnt vmcnt(6)
	v_add_f32_e32 v0, v0, v1
	v_add_f32_e32 v1, v2, v3
	v_add_f32_e32 v0, v0, v1
	v_fmamk_f32 v0, v0, 0x3a800000, v228
	v_mul_f32_e32 v1, 0x4f800000, v0
	v_cmp_gt_f32_e32 vcc, s36, v0
	s_nop 1
	v_cndmask_b32_e32 v0, v0, v1, vcc
	v_sqrt_f32_e32 v1, v0
	s_nop 0
	v_add_u32_e32 v2, -1, v1
	v_fma_f32 v3, -v2, v1, v0
	v_cmp_ge_f32_e64 s[4:5], 0, v3
	v_add_u32_e32 v3, 1, v1
	s_nop 0
	v_cndmask_b32_e64 v2, v1, v2, s[4:5]
	v_fma_f32 v1, -v3, v1, v0
	v_cmp_lt_f32_e64 s[4:5], 0, v1
	s_nop 1
	v_cndmask_b32_e64 v1, v2, v3, s[4:5]
	v_mul_f32_e32 v2, 0x37800000, v1
	v_cndmask_b32_e32 v1, v1, v2, vcc
	v_cmp_class_f32_e32 vcc, v0, v229
	s_nop 1
	v_cndmask_b32_e32 v0, v1, v0, vcc
	v_div_scale_f32 v1, s[4:5], v0, v0, 1.0
	v_rcp_f32_e32 v2, v1
	s_nop 0
	v_fma_f32 v3, -v1, v2, 1.0
	v_fmac_f32_e32 v2, v3, v2
	v_div_scale_f32 v3, vcc, 1.0, v0, 1.0
	v_mul_f32_e32 v12, v3, v2
	v_fma_f32 v13, -v1, v12, v3
	v_fmac_f32_e32 v12, v13, v2
	v_fma_f32 v1, -v1, v12, v3
	v_div_fmas_f32 v1, v1, v2, v12
	v_div_fixup_f32 v0, v1, v0, 1.0
	v_lshl_add_u32 v1, v4, 2, 0
	v_add_u32_e32 v1, 0x22200, v1
	ds_write_b32 v1, v0

; #define PG8_STAGE(bufoff, gbase, voff) do { _Pragma("unroll") for (int _i = 0; _i < 2; ++_i) \
;         __builtin_amdgcn_global_load_lds((const unsigned*)((const char*)(gbase) + (voff)[_i]), (PG8_LAS unsigned*)(lds + (bufoff) + ldsw + _i * 8192), 16, 0, 0); } while (0)
; #define PG8_WAIT_V(n) asm volatile("s_waitcnt vmcnt(" #n ")" ::: "memory")
; #define PG8_BAR __builtin_amdgcn_s_barrier()
;     __device__ __forceinline__ void init(f32x4 (&acc)[2][2][4][2], const Unit& u, int wr, int wc, int fr, int fq) const {
;         const int col0 = u.pn * BM + wc * 32 + 8 * fq;
; #pragma unroll
;         for (int ai = 0; ai < 2; ++ai)
; #pragma unroll
;             for (int m = 0; m < 4; ++m) { const size_t off = (size_t)(u.pm * BM + ai * HALF + wr * 64 + m * 16 + fr) * ldc + col0;
; #pragma unroll
;                 for (int bj = 0; bj < 2; ++bj) { const size_t p = off + bj * HALF;
;                     if (base32) { acc[ai][bj][m][0] = *(const f32x4*)(base32 + p); acc[ai][bj][m][1] = *(const f32x4*)(base32 + p + 4); }
;                     else { const u32x4 r = *(const u32x4*)(xn + p); acc[ai][bj][m][0] = (f32x4){__uint_as_float(r.x << 16), __uint_as_float(r.x & 0xffff0000u), __uint_as_float(r.y << 16), __uint_as_float(r.y & 0xffff0000u)};
;                         acc[ai][bj][m][1] = (f32x4){__uint_as_float(r.z << 16), __uint_as_float(r.z & 0xffff0000u), __uint_as_float(r.w << 16), __uint_as_float(r.w & 0xffff0000u)}; } } }
; template <class Epi, class Sched, bool ALIGN_EPI = false, bool SP2 = false>
; __device__ __forceinline__ void gemm_phase(PG8_LAS unsigned char* lds, const Gemm g, const Sched& S, const Epi& E, const int tid_in) {
;     ...
;     const char* cA = (const char*)g.A + (size_t)cur.pm * tstepA + (size_t)(cur.pm >> 3) * g.abx; const char* cB = (const char*)g.Bt + (size_t)cur.pn * tstepB;
;     S.a_ready(cur);
;     if constexpr (SP2) {
;         PG8_STAGE(PG8_SB(0, 0), cB, voffB); PG8_STAGE(PG8_SB(0, 1), cB + hstepB, voffB); PG8_STAGE(PG8_SA(0, 0), cA, voffA); PG8_STAGE(PG8_SA(0, 1), cA + hstepA, voffA);
;         if (wr == 1) PG8_BAR;
;         PG8_WAIT_V(2); PG8_BAR;
;         PG8_STAGE(PG8_SB(1, 0), cB + kstep, voffB); PG8_STAGE(PG8_SA(1, 0), cA + kstep, voffA); PG8_STAGE(PG8_SB(1, 1), cB + hstepB + kstep, voffB);
;         PG8_WAIT_V(6); PG8_BAR;
.LBB0_781:
	s_cmp_le_i32 s92, s48
	s_cselect_b64 s[0:1], -1, 0
	s_cmp_lt_i32 s48, s93
	s_cselect_b64 s[4:5], -1, 0
	s_and_b64 s[0:1], s[0:1], s[4:5]
	s_andn2_b64 vcc, exec, s[0:1]
	s_cbranch_vccnz .LBB0_831
	s_mov_b32 s0, -1
	v_readlane_b32 s4, v254, 14
	s_waitcnt vmcnt(0)
	v_mbcnt_lo_u32_b32 v0, s0, 0
	v_mbcnt_hi_u32_b32 v1, s0, v0
	s_load_dwordx2 s[0:1], s[94:95], 0x88
	v_add_u32_e32 v0, s97, v1
	v_readlane_b32 s5, v254, 15
	s_andn2_b64 vcc, exec, s[4:5]
	v_readfirstlane_b32 s6, v0
	s_cbranch_vccnz .LBB0_820
	s_waitcnt lgkmcnt(0)
	s_add_u32 s48, s0, 0x9400000
	s_addc_u32 s54, s1, 0
	s_lshl_b32 s4, s86, 22
	s_add_u32 s4, s0, s4
	s_addc_u32 s5, s1, 0
	s_add_u32 s55, s4, 0x1800000
	v_bfe_u32 v147, v1, 4, 2
	v_and_b32_e32 v146, 15, v1
	v_lshlrev_b32_e32 v1, 4, v0
	s_addc_u32 s56, s5, 0
	v_add_u32_e32 v2, 0x2000, v1
	s_add_u32 s12, s0, 0x7400000
	v_ashrrev_i32_e32 v3, 31, v2
	s_addc_u32 s13, s1, 0
	s_ashr_i32 s5, s6, 6
	v_lshrrev_b32_e32 v3, 22, v3
	s_and_b32 s8, s5, 3
	v_add_u32_e32 v3, v2, v3
	s_lshl_b32 s57, s5, 10
	s_lshl_b32 s9, s8, 5
	v_ashrrev_i32_e32 v149, 10, v3
	v_readlane_b32 s5, v254, 32
	s_ashr_i32 s4, s6, 8
	v_lshlrev_b32_e32 v148, 3, v147
	v_mul_i32_i24_e32 v3, 0x400, v149
	s_or_b32 s5, s5, s9
	v_lshl_or_b32 v144, s4, 6, v146
	v_sub_u32_e32 v10, v2, v3
	v_or_b32_e32 v2, s5, v148
	v_readlane_b32 s5, v254, 36
	v_lshrrev_b32_e32 v11, 4, v10
	v_ashrrev_i32_e32 v3, 31, v2
	v_add_u32_e32 v8, s5, v144
	v_ashrrev_i32_e32 v9, 31, v8
	v_lshlrev_b64 v[4:5], 11, v[8:9]
	v_bitop3_b32 v9, v11, v10, 32 bitop3:0x6c
	v_ashrrev_i32_e32 v10, 31, v9
	v_lshrrev_b32_e32 v10, 26, v10
	v_add_u32_e32 v10, v9, v10
	v_lshlrev_b32_e32 v11, 3, v149
	v_ashrrev_i32_e32 v150, 6, v10
	v_and_b32_e32 v11, -16, v11
	v_add_u32_e32 v11, v150, v11
	v_and_b32_e32 v12, 3, v150
	s_mov_b32 s5, 0xfffe0
	v_lshl_add_u64 v[4:5], s[12:13], 0, v[4:5]
	v_lshlrev_b64 v[34:35], 1, v[2:3]
	v_and_or_b32 v16, v11, s5, v12
	v_lshrrev_b32_e32 v12, 2, v11
	v_and_b32_e32 v10, 0xc0, v10
	v_lshl_add_u64 v[2:3], v[4:5], 0, v[34:35]
	v_and_b32_e32 v17, 4, v12
	v_lshlrev_b32_e32 v12, 1, v11
	v_sub_u32_e32 v9, v9, v10
	global_load_dwordx4 v[4:7], v[2:3], off
	v_and_b32_e32 v18, 24, v12
	global_load_dwordx4 v[12:15], v[2:3], off offset:256
	v_lshlrev_b32_e32 v3, 5, v149
	v_ashrrev_i16_sdwa v9, v233, sext(v9) dst_sel:DWORD dst_unused:UNUSED_PAD src0_sel:DWORD src1_sel:BYTE_0
	v_and_b32_e32 v3, 32, v3
	v_bfe_i32 v151, v9, 0, 16
	v_or3_b32 v2, v16, v17, v18
	v_add_lshl_u32 v9, v3, v151, 1
	v_lshl_add_u32 v112, v2, 12, v9
	v_lshl_add_u32 v132, v11, 13, v9
	v_bfe_i32 v9, v0, 27, 1
	v_lshrrev_b32_e32 v9, 22, v9
	v_add_u32_e32 v9, v1, v9
	v_and_b32_e32 v9, 0xfffffc00, v9
	v_add_u32_e32 v2, 16, v8
	v_sub_u32_e32 v1, v1, v9
	v_ashrrev_i32_e32 v3, 31, v2
	v_lshrrev_b32_e32 v9, 4, v1
	v_lshlrev_b64 v[2:3], 11, v[2:3]
	v_bitop3_b32 v9, v9, v1, 32 bitop3:0x6c
	v_lshl_add_u64 v[2:3], s[12:13], 0, v[2:3]
	v_ashrrev_i32_e32 v1, 31, v9
	v_lshl_add_u64 v[2:3], v[2:3], 0, v[34:35]
	v_lshrrev_b32_e32 v1, 26, v1
	global_load_dwordx4 v[20:23], v[2:3], off
	global_load_dwordx4 v[28:31], v[2:3], off offset:256
	v_add_u32_e32 v2, v9, v1
	v_ashrrev_i32_e32 v1, 31, v0
	v_lshrrev_b32_e32 v1, 26, v1
	v_add_u32_e32 v0, v0, v1
	v_ashrrev_i32_e32 v153, 6, v0
	v_add_u32_e32 v0, 32, v8
	v_ashrrev_i32_e32 v1, 31, v0
	v_lshlrev_b64 v[0:1], 11, v[0:1]
	v_ashrrev_i32_e32 v152, 6, v2
	v_lshl_add_u64 v[0:1], s[12:13], 0, v[0:1]
	v_and_b32_e32 v2, 0xc0, v2
	v_lshl_add_u64 v[0:1], v[0:1], 0, v[34:35]
	v_sub_u32_e32 v2, v9, v2
	global_load_dwordx4 v[36:39], v[0:1], off
	global_load_dwordx4 v[44:47], v[0:1], off offset:256
	v_ashrrev_i16_sdwa v0, v233, sext(v2) dst_sel:DWORD dst_unused:UNUSED_PAD src0_sel:DWORD src1_sel:BYTE_0
	v_bfe_i32 v154, v0, 0, 16
	v_add_u32_e32 v0, 48, v8
	v_lshlrev_b32_e32 v3, 3, v153
	v_ashrrev_i32_e32 v1, 31, v0
	v_and_b32_e32 v3, -16, v3
	v_lshlrev_b64 v[0:1], 11, v[0:1]
	v_add_u32_e32 v3, v152, v3
	v_and_b32_e32 v10, 3, v152
	v_lshl_add_u64 v[0:1], s[12:13], 0, v[0:1]
	v_and_or_b32 v10, v3, s5, v10
	v_lshl_add_u64 v[8:9], v[0:1], 0, v[34:35]
	v_readlane_b32 s5, v254, 33
	global_load_dwordx4 v[52:55], v[8:9], off
	global_load_dwordx4 v[60:63], v[8:9], off offset:256
	v_add_u32_e32 v8, s5, v144
	v_ashrrev_i32_e32 v9, 31, v8
	v_lshrrev_b32_e32 v11, 2, v3
	v_lshlrev_b32_e32 v16, 1, v3
	v_lshlrev_b64 v[8:9], 11, v[8:9]
	v_and_b32_e32 v11, 4, v11
	v_and_b32_e32 v16, 24, v16
	v_lshl_add_u64 v[8:9], s[12:13], 0, v[8:9]
	v_or3_b32 v10, v10, v11, v16
	v_lshl_add_u64 v[16:17], v[8:9], 0, v[34:35]
	v_readlane_b32 s5, v254, 34
	global_load_dwordx4 v[68:71], v[16:17], off
	global_load_dwordx4 v[76:79], v[16:17], off offset:256
	v_add_u32_e32 v16, s5, v144
	v_readlane_b32 s5, v254, 35
	v_ashrrev_i32_e32 v17, 31, v16
	v_lshlrev_b64 v[16:17], 11, v[16:17]
	v_add_u32_e32 v26, s5, v144
	v_readlane_b32 s5, v254, 37
	v_ashrrev_i32_e32 v27, 31, v26
	v_lshlrev_b64 v[26:27], 11, v[26:27]
	v_add_u32_e32 v40, s5, v144
	v_ashrrev_i32_e32 v41, 31, v40
	v_lshlrev_b64 v[40:41], 11, v[40:41]
	v_lshl_add_u64 v[16:17], s[12:13], 0, v[16:17]
	v_lshl_add_u64 v[26:27], s[12:13], 0, v[26:27]
	v_lshl_add_u64 v[40:41], s[12:13], 0, v[40:41]
	v_lshl_add_u64 v[24:25], v[16:17], 0, v[34:35]
	v_lshl_add_u64 v[32:33], v[26:27], 0, v[34:35]
	v_lshl_add_u64 v[42:43], v[40:41], 0, v[34:35]
	global_load_dwordx4 v[84:87], v[24:25], off
	global_load_dwordx4 v[92:95], v[24:25], off offset:256
	global_load_dwordx4 v[100:103], v[32:33], off
	global_load_dwordx4 v[108:111], v[32:33], off offset:256
	global_load_dwordx4 v[120:123], v[42:43], off
	global_load_dwordx4 v[128:131], v[42:43], off offset:256
	v_lshlrev_b32_e32 v11, 5, v153
	v_readlane_b32 s14, v254, 48
	v_and_b32_e32 v11, 32, v11
	v_readlane_b32 s15, v254, 49
	s_add_u32 s46, s55, s14
	v_add_lshl_u32 v2, v11, v154, 1
	s_addc_u32 s47, s56, s15
	s_add_i32 s58, s57, 0
	v_lshl_add_u32 v114, v10, 12, v2
	v_lshl_add_u32 v134, v3, 13, v2
	s_add_i32 m0, s58, 0x10000
	s_nop 0
	global_load_lds_dwordx4 v114, s[46:47]
	s_add_i32 m0, s58, 0x12000
	v_readlane_b32 s14, v254, 46
	v_readlane_b32 s15, v254, 47
	s_add_u32 s42, s48, s14
	s_addc_u32 s43, s54, s15
	s_add_u32 s14, s46, 0x80000
	global_load_lds_dwordx4 v112, s[46:47]
	s_addc_u32 s15, s47, 0
	s_add_i32 m0, s58, 0x14000
	s_add_i32 s59, s58, 0x2000
	global_load_lds_dwordx4 v114, s[14:15]
	s_add_i32 m0, s58, 0x16000
	v_mov_b32_e32 v113, v115
	global_load_lds_dwordx4 v112, s[14:15]
	s_mov_b32 m0, s58
	s_add_u32 s14, s42, 0x100000
	global_load_lds_dwordx4 v134, s[42:43]
	s_mov_b32 m0, s59
	s_addc_u32 s15, s43, 0
	s_add_i32 s60, s58, 0x4000
	global_load_lds_dwordx4 v132, s[42:43]
	s_mov_b32 m0, s60
	s_add_i32 s61, s58, 0x6000
	global_load_lds_dwordx4 v134, s[14:15]
	s_mov_b32 m0, s61
	v_mov_b32_e32 v135, v115
	global_load_lds_dwordx4 v132, s[14:15]
	s_waitcnt vmcnt(23)
; #define PG8_STAGE(bufoff, gbase, voff) do { _Pragma("unroll") for (int _i = 0; _i < 2; ++_i) \
;         __builtin_amdgcn_global_load_lds((const unsigned*)((const char*)(gbase) + (voff)[_i]), (PG8_LAS unsigned*)(lds + (bufoff) + ldsw + _i * 8192), 16, 0, 0); } while (0)
; #define PG8_BAR __builtin_amdgcn_s_barrier()
;     __device__ __forceinline__ void init(f32x4 (&acc)[2][2][4][2], const Unit& u, int wr, int wc, int fr, int fq) const {
;     ...
;                 for (int bj = 0; bj < 2; ++bj) { const size_t p = off + bj * HALF;
;                     if (base32) { acc[ai][bj][m][0] = *(const f32x4*)(base32 + p); acc[ai][bj][m][1] = *(const f32x4*)(base32 + p + 4); }
;                     else { const u32x4 r = *(const u32x4*)(xn + p); acc[ai][bj][m][0] = (f32x4){__uint_as_float(r.x << 16), __uint_as_float(r.x & 0xffff0000u), __uint_as_float(r.y << 16), __uint_as_float(r.y & 0xffff0000u)};
;                         acc[ai][bj][m][1] = (f32x4){__uint_as_float(r.z << 16), __uint_as_float(r.z & 0xffff0000u), __uint_as_float(r.w << 16), __uint_as_float(r.w & 0xffff0000u)}; } } }
; #pragma unroll
;         for (int ai = 0; ai < 2; ++ai)
; #pragma unroll
;             for (int bj = 0; bj < 2; ++bj)
; #pragma unroll
;                 for (int m = 0; m < 4; ++m) asm volatile("" : "+v"(acc[ai][bj][m][0]), "+v"(acc[ai][bj][m][1]));
; template <class Epi, class Sched, bool ALIGN_EPI = false, bool SP2 = false>
; __device__ __forceinline__ void gemm_phase(PG8_LAS unsigned char* lds, const Gemm g, const Sched& S, const Epi& E, const int tid_in) {
;     ...
;         PG8_STAGE(PG8_SB(0, 0), cB, voffB); PG8_STAGE(PG8_SB(0, 1), cB + hstepB, voffB); PG8_STAGE(PG8_SA(0, 0), cA, voffA); PG8_STAGE(PG8_SA(0, 1), cA + hstepA, voffA);
;         if (wr == 1) PG8_BAR;
	v_lshlrev_b32_e32 v0, 16, v4
	v_and_b32_e32 v1, 0xffff0000, v4
	v_lshlrev_b32_e32 v2, 16, v5
	v_and_b32_e32 v3, 0xffff0000, v5
	v_lshlrev_b32_e32 v4, 16, v6
	v_and_b32_e32 v5, 0xffff0000, v6
	v_lshlrev_b32_e32 v6, 16, v7
	v_and_b32_e32 v7, 0xffff0000, v7
	s_waitcnt vmcnt(22)
	v_lshlrev_b32_e32 v8, 16, v12
	v_and_b32_e32 v9, 0xffff0000, v12
	v_lshlrev_b32_e32 v10, 16, v13
	v_and_b32_e32 v11, 0xffff0000, v13
	v_lshlrev_b32_e32 v12, 16, v14
	v_and_b32_e32 v13, 0xffff0000, v14
	v_lshlrev_b32_e32 v14, 16, v15
	v_and_b32_e32 v15, 0xffff0000, v15
	s_waitcnt vmcnt(21)
	v_lshlrev_b32_e32 v16, 16, v20
	v_and_b32_e32 v17, 0xffff0000, v20
	v_lshlrev_b32_e32 v18, 16, v21
	v_and_b32_e32 v19, 0xffff0000, v21
	v_lshlrev_b32_e32 v20, 16, v22
	v_and_b32_e32 v21, 0xffff0000, v22
	v_lshlrev_b32_e32 v22, 16, v23
	v_and_b32_e32 v23, 0xffff0000, v23
	s_waitcnt vmcnt(20)
	v_lshlrev_b32_e32 v24, 16, v28
	v_and_b32_e32 v25, 0xffff0000, v28
	v_lshlrev_b32_e32 v26, 16, v29
	v_and_b32_e32 v27, 0xffff0000, v29
	v_lshlrev_b32_e32 v28, 16, v30
	v_and_b32_e32 v29, 0xffff0000, v30
	v_lshlrev_b32_e32 v30, 16, v31
	v_and_b32_e32 v31, 0xffff0000, v31
	s_waitcnt vmcnt(19)
	v_lshlrev_b32_e32 v32, 16, v36
	v_and_b32_e32 v33, 0xffff0000, v36
	v_lshlrev_b32_e32 v34, 16, v37
	v_and_b32_e32 v35, 0xffff0000, v37
	v_lshlrev_b32_e32 v36, 16, v38
	v_and_b32_e32 v37, 0xffff0000, v38
	v_lshlrev_b32_e32 v38, 16, v39
	v_and_b32_e32 v39, 0xffff0000, v39
	s_waitcnt vmcnt(18)
	v_lshlrev_b32_e32 v40, 16, v44
	v_and_b32_e32 v41, 0xffff0000, v44
	v_lshlrev_b32_e32 v42, 16, v45
	v_and_b32_e32 v43, 0xffff0000, v45
	v_lshlrev_b32_e32 v44, 16, v46
	v_and_b32_e32 v45, 0xffff0000, v46
	v_lshlrev_b32_e32 v46, 16, v47
	v_and_b32_e32 v47, 0xffff0000, v47
	s_waitcnt vmcnt(17)
	v_lshlrev_b32_e32 v48, 16, v52
	v_and_b32_e32 v49, 0xffff0000, v52
	v_lshlrev_b32_e32 v50, 16, v53
	v_and_b32_e32 v51, 0xffff0000, v53
	v_lshlrev_b32_e32 v52, 16, v54
	v_and_b32_e32 v53, 0xffff0000, v54
	v_lshlrev_b32_e32 v54, 16, v55
	v_and_b32_e32 v55, 0xffff0000, v55
	s_waitcnt vmcnt(16)
	v_lshlrev_b32_e32 v56, 16, v60
	v_and_b32_e32 v57, 0xffff0000, v60
	v_lshlrev_b32_e32 v58, 16, v61
	v_and_b32_e32 v59, 0xffff0000, v61
	v_lshlrev_b32_e32 v60, 16, v62
	v_and_b32_e32 v61, 0xffff0000, v62
	v_lshlrev_b32_e32 v62, 16, v63
	v_and_b32_e32 v63, 0xffff0000, v63
	s_waitcnt vmcnt(15)
	v_lshlrev_b32_e32 v64, 16, v68
	v_and_b32_e32 v65, 0xffff0000, v68
	v_lshlrev_b32_e32 v66, 16, v69
	v_and_b32_e32 v67, 0xffff0000, v69
	v_lshlrev_b32_e32 v68, 16, v70
	v_and_b32_e32 v69, 0xffff0000, v70
	v_lshlrev_b32_e32 v70, 16, v71
	v_and_b32_e32 v71, 0xffff0000, v71
	s_waitcnt vmcnt(14)
	v_lshlrev_b32_e32 v72, 16, v76
	v_and_b32_e32 v73, 0xffff0000, v76
	v_lshlrev_b32_e32 v74, 16, v77
	v_and_b32_e32 v75, 0xffff0000, v77
	v_lshlrev_b32_e32 v76, 16, v78
	v_and_b32_e32 v77, 0xffff0000, v78
	v_lshlrev_b32_e32 v78, 16, v79
	v_and_b32_e32 v79, 0xffff0000, v79
	s_waitcnt vmcnt(13)
	v_lshlrev_b32_e32 v80, 16, v84
	v_and_b32_e32 v81, 0xffff0000, v84
	v_lshlrev_b32_e32 v82, 16, v85
	v_and_b32_e32 v83, 0xffff0000, v85
	v_lshlrev_b32_e32 v84, 16, v86
	v_and_b32_e32 v85, 0xffff0000, v86
	v_lshlrev_b32_e32 v86, 16, v87
	v_and_b32_e32 v87, 0xffff0000, v87
	s_waitcnt vmcnt(12)
	v_lshlrev_b32_e32 v88, 16, v92
	v_and_b32_e32 v89, 0xffff0000, v92
	v_lshlrev_b32_e32 v90, 16, v93
	v_and_b32_e32 v91, 0xffff0000, v93
	v_lshlrev_b32_e32 v92, 16, v94
	v_and_b32_e32 v93, 0xffff0000, v94
	v_lshlrev_b32_e32 v94, 16, v95
	v_and_b32_e32 v95, 0xffff0000, v95
	s_waitcnt vmcnt(11)
	v_lshlrev_b32_e32 v96, 16, v100
	v_and_b32_e32 v97, 0xffff0000, v100
	v_lshlrev_b32_e32 v98, 16, v101
	v_and_b32_e32 v99, 0xffff0000, v101
	v_lshlrev_b32_e32 v100, 16, v102
	v_and_b32_e32 v101, 0xffff0000, v102
	v_lshlrev_b32_e32 v102, 16, v103
	v_and_b32_e32 v103, 0xffff0000, v103
	s_waitcnt vmcnt(10)
	v_lshlrev_b32_e32 v104, 16, v108
	v_and_b32_e32 v105, 0xffff0000, v108
	v_lshlrev_b32_e32 v106, 16, v109
	v_and_b32_e32 v107, 0xffff0000, v109
	v_lshlrev_b32_e32 v108, 16, v110
	v_and_b32_e32 v109, 0xffff0000, v110
	v_lshlrev_b32_e32 v110, 16, v111
	v_and_b32_e32 v111, 0xffff0000, v111
	s_waitcnt vmcnt(9)
	v_lshlrev_b32_e32 v116, 16, v120
	v_and_b32_e32 v117, 0xffff0000, v120
	v_lshlrev_b32_e32 v118, 16, v121
	v_and_b32_e32 v119, 0xffff0000, v121
	v_lshlrev_b32_e32 v120, 16, v122
	v_and_b32_e32 v121, 0xffff0000, v122
	v_lshlrev_b32_e32 v122, 16, v123
	v_and_b32_e32 v123, 0xffff0000, v123
	s_waitcnt vmcnt(8)
	v_lshlrev_b32_e32 v124, 16, v128
	v_and_b32_e32 v125, 0xffff0000, v128
	v_lshlrev_b32_e32 v126, 16, v129
	v_and_b32_e32 v127, 0xffff0000, v129
	v_lshlrev_b32_e32 v128, 16, v130
	v_and_b32_e32 v129, 0xffff0000, v130
	v_lshlrev_b32_e32 v130, 16, v131
	v_and_b32_e32 v131, 0xffff0000, v131
	v_mov_b32_e32 v133, v115
	s_cmp_eq_u32 s4, 1
	v_lshl_add_u64 v[142:143], s[46:47], 0, v[114:115]
	v_lshl_add_u64 v[140:141], s[46:47], 0, v[112:113]
	v_lshl_add_u64 v[136:137], s[42:43], 0, v[134:135]
	s_cselect_b64 s[18:19], -1, 0
	s_cmp_lg_u32 s4, 1
	v_lshl_add_u64 v[138:139], s[42:43], 0, v[132:133]
	s_cbranch_scc1 .LBB0_785
	s_barrier

;     __device__ __forceinline__ void pre(int tid) const { if (tid < BM) rsl_w[tid] = 1.0f / sqrtf(((rs_raw[0] + rs_raw[1]) + (rs_raw[2] + rs_raw[3])) * (1.0f / 1024.0f) + 1e-6f); }
;     __device__ __forceinline__ void pre(int tid) const { if (tid < BM) rsl_w[tid] = 1.0f / sqrtf(((rs_raw[0] + rs_raw[1]) + (rs_raw[2] + rs_raw[3])) * (1.0f / 1024.0f) + 1e-6f); }
; #define PG8_STAGE(bufoff, gbase, voff) do { _Pragma("unroll") for (int _i = 0; _i < 2; ++_i) \
;         __builtin_amdgcn_global_load_lds((const unsigned*)((const char*)(gbase) + (voff)[_i]), (PG8_LAS unsigned*)(lds + (bufoff) + ldsw + _i * 8192), 16, 0, 0); } while (0)
; #define PG8_WAIT_V(n) asm volatile("s_waitcnt vmcnt(" #n ")" ::: "memory")
; #define PG8_BAR __builtin_amdgcn_s_barrier()
; template <class Epi, class Sched, bool ALIGN_EPI = false, bool SP2 = false>
; __device__ __forceinline__ void gemm_phase(PG8_LAS unsigned char* lds, const Gemm g, const Sched& S, const Epi& E, const int tid_in) {
;     ...
;         PG8_STAGE(PG8_SB(0, 0), cB, voffB); PG8_STAGE(PG8_SB(0, 1), cB + hstepB, voffB); PG8_STAGE(PG8_SA(0, 0), cA, voffA); PG8_STAGE(PG8_SA(0, 1), cA + hstepA, voffA);
;         if (wr == 1) PG8_BAR;
;         PG8_WAIT_V(2); PG8_BAR;
;         PG8_STAGE(PG8_SB(1, 0), cB + kstep, voffB); PG8_STAGE(PG8_SA(1, 0), cA + kstep, voffA); PG8_STAGE(PG8_SB(1, 1), cB + hstepB + kstep, voffB);
;         PG8_WAIT_V(6); PG8_BAR;
;     } else {
;         PG8_STAGE(PG8_SB(0, 0), cB, voffB); PG8_STAGE(PG8_SA(0, 0), cA, voffA); PG8_STAGE(PG8_SB(0, 1), cB + hstepB, voffB); PG8_STAGE(PG8_SA(0, 1), cA + hstepA, voffA);
;         if (wr == 1) PG8_BAR;
;         PG8_WAIT_V(4); PG8_BAR;
;         PG8_STAGE(PG8_SB(1, 0), cB + kstep, voffB); PG8_STAGE(PG8_SA(1, 0), cA + kstep, voffA); PG8_STAGE(PG8_SB(1, 1), cB + hstepB + kstep, voffB);
;         PG8_WAIT_V(6); PG8_BAR;
;     }
;     if constexpr (Epi::HAS_PRE) E.pre(tid);
.LBB0_844:
	v_mov_b32_e32 v159, v115
	v_lshl_add_u64 v[12:13], s[38:39], 0, v[114:115]
	v_mov_b32_e32 v113, v115
	v_lshl_add_u64 v[14:15], s[38:39], 0, v[158:159]
	s_add_i32 m0, s47, 0x18000
	v_lshl_add_u64 v[12:13], v[12:13], 0, s[10:11]
	v_mov_b32_e32 v157, v115
	v_lshl_add_u64 v[16:17], s[6:7], 0, v[112:113]
	s_waitcnt vmcnt(2)
	s_barrier
	global_load_lds_dwordx4 v[12:13], off
	v_lshl_add_u64 v[12:13], v[14:15], 0, s[10:11]
	s_add_i32 m0, s47, 0x1a000
	s_add_i32 s53, s47, 0x8000
	s_add_i32 s54, s47, 0xa000
	v_lshl_add_u64 v[18:19], s[6:7], 0, v[156:157]
	global_load_lds_dwordx4 v[12:13], off
	v_lshl_add_u64 v[12:13], v[16:17], 0, s[10:11]
	s_mov_b32 m0, s53
	s_add_u32 s12, s38, 0x40080
	global_load_lds_dwordx4 v[12:13], off
	v_lshl_add_u64 v[12:13], v[18:19], 0, s[10:11]
	s_mov_b32 m0, s54
	s_addc_u32 s13, s39, 0
	global_load_lds_dwordx4 v[12:13], off
	s_add_i32 m0, s47, 0x1c000
	v_lshl_add_u64 v[12:13], s[12:13], 0, v[114:115]
	global_load_lds_dwordx4 v[12:13], off
	v_lshl_add_u64 v[12:13], s[12:13], 0, v[158:159]
	s_add_i32 m0, s47, 0x1e000
	s_nop 0
	global_load_lds_dwordx4 v[12:13], off
	s_waitcnt vmcnt(6)
	s_barrier
	s_and_saveexec_b64 s[12:13], s[4:5]
	s_cbranch_execz .LBB0_846
	s_waitcnt vmcnt(6)
	v_add_f32_e32 v0, v0, v1
	v_add_f32_e32 v1, v2, v3
	v_add_f32_e32 v0, v0, v1
	v_fmamk_f32 v0, v0, 0x3a800000, v228
	v_mul_f32_e32 v1, 0x4f800000, v0
	v_cmp_gt_f32_e32 vcc, s36, v0
	s_nop 1
	v_cndmask_b32_e32 v0, v0, v1, vcc
	v_sqrt_f32_e32 v1, v0
	s_nop 0
	v_add_u32_e32 v2, -1, v1
	v_fma_f32 v3, -v2, v1, v0
	v_cmp_ge_f32_e64 s[4:5], 0, v3
	v_add_u32_e32 v3, 1, v1
	s_nop 0
	v_cndmask_b32_e64 v2, v1, v2, s[4:5]
	v_fma_f32 v1, -v3, v1, v0
	v_cmp_lt_f32_e64 s[4:5], 0, v1
	s_nop 1
	v_cndmask_b32_e64 v1, v2, v3, s[4:5]
	v_mul_f32_e32 v2, 0x37800000, v1
	v_cndmask_b32_e32 v1, v1, v2, vcc
	v_cmp_class_f32_e32 vcc, v0, v229
	s_nop 1
	v_cndmask_b32_e32 v0, v1, v0, vcc
	v_div_scale_f32 v1, s[4:5], v0, v0, 1.0
	v_rcp_f32_e32 v2, v1
	s_nop 0
	v_fma_f32 v3, -v1, v2, 1.0
	v_fmac_f32_e32 v2, v3, v2
	v_div_scale_f32 v3, vcc, 1.0, v0, 1.0
	v_mul_f32_e32 v12, v3, v2
	v_fma_f32 v13, -v1, v12, v3
	v_fmac_f32_e32 v12, v13, v2
	v_fma_f32 v1, -v1, v12, v3
	v_div_fmas_f32 v1, v1, v2, v12
	v_div_fixup_f32 v0, v1, v0, 1.0
	v_lshl_add_u32 v1, v4, 2, 0
	v_add_u32_e32 v1, 0x22200, v1
	ds_write_b32 v1, v0

; __device__ __forceinline__ void xcd_barrier(const XcdBarrier& b, const bool local_only = false) {
;     ...
;     }
;     __syncthreads();
; }
.Lxb_ld_exit_13:
.LBB0_956:
	s_or_b64 exec, exec, s[8:9]
	s_waitcnt lgkmcnt(0)
	s_barrier

; #define PG8_STAGE(bufoff, gbase, voff) do { _Pragma("unroll") for (int _i = 0; _i < 2; ++_i) \
;         __builtin_amdgcn_global_load_lds((const unsigned*)((const char*)(gbase) + (voff)[_i]), (PG8_LAS unsigned*)(lds + (bufoff) + ldsw + _i * 8192), 16, 0, 0); } while (0)
; #define PG8_WAIT_V(n) asm volatile("s_waitcnt vmcnt(" #n ")" ::: "memory")
; #define PG8_BAR __builtin_amdgcn_s_barrier()
;     __device__ __forceinline__ void init(f32x4 (&acc)[2][2][4][2], const Unit& u, int wr, int wc, int fr, int fq) const {
;         const int col0 = u.pn * BM + wc * 32 + 8 * fq;
; #pragma unroll
;         for (int ai = 0; ai < 2; ++ai)
; #pragma unroll
;             for (int m = 0; m < 4; ++m) { const size_t off = (size_t)(u.pm * BM + ai * HALF + wr * 64 + m * 16 + fr) * ldc + col0;
; #pragma unroll
;                 for (int bj = 0; bj < 2; ++bj) { const size_t p = off + bj * HALF;
;                     if (base32) { acc[ai][bj][m][0] = *(const f32x4*)(base32 + p); acc[ai][bj][m][1] = *(const f32x4*)(base32 + p + 4); }
;                     else { const u32x4 r = *(const u32x4*)(xn + p); acc[ai][bj][m][0] = (f32x4){__uint_as_float(r.x << 16), __uint_as_float(r.x & 0xffff0000u), __uint_as_float(r.y << 16), __uint_as_float(r.y & 0xffff0000u)};
;                         acc[ai][bj][m][1] = (f32x4){__uint_as_float(r.z << 16), __uint_as_float(r.z & 0xffff0000u), __uint_as_float(r.w << 16), __uint_as_float(r.w & 0xffff0000u)}; } } }
; template <class Epi, class Sched, bool ALIGN_EPI = false, bool SP2 = false>
; __device__ __forceinline__ void gemm_phase(PG8_LAS unsigned char* lds, const Gemm g, const Sched& S, const Epi& E, const int tid_in) {
;     ...
;     const char* cA = (const char*)g.A + (size_t)cur.pm * tstepA + (size_t)(cur.pm >> 3) * g.abx; const char* cB = (const char*)g.Bt + (size_t)cur.pn * tstepB;
;     S.a_ready(cur);
;     if constexpr (SP2) {
;         PG8_STAGE(PG8_SB(0, 0), cB, voffB); PG8_STAGE(PG8_SB(0, 1), cB + hstepB, voffB); PG8_STAGE(PG8_SA(0, 0), cA, voffA); PG8_STAGE(PG8_SA(0, 1), cA + hstepA, voffA);
;         if (wr == 1) PG8_BAR;
;         PG8_WAIT_V(2); PG8_BAR;
;         PG8_STAGE(PG8_SB(1, 0), cB + kstep, voffB); PG8_STAGE(PG8_SA(1, 0), cA + kstep, voffA); PG8_STAGE(PG8_SB(1, 1), cB + hstepB + kstep, voffB);
;         PG8_WAIT_V(6); PG8_BAR;
.LBB0_962:
	s_load_dwordx2 s[0:1], s[94:95], 0x88
	s_waitcnt vmcnt(0)
	v_mbcnt_lo_u32_b32 v0, s4, 0
	v_mbcnt_hi_u32_b32 v1, s4, v0
	v_readlane_b32 s4, v254, 14
	v_add_u32_e32 v0, s97, v1
	v_readlane_b32 s5, v254, 15
	s_andn2_b64 vcc, exec, s[4:5]
	v_readfirstlane_b32 s6, v0
	s_cbranch_vccnz .LBB0_1065
	s_waitcnt lgkmcnt(0)
	s_add_u32 s18, s0, 0x7400000
	s_addc_u32 s19, s1, 0
	s_ashr_i32 s5, s6, 6
	s_and_b32 s8, s5, 3
	v_bfe_u32 v147, v1, 4, 2
	s_ashr_i32 s4, s6, 8
	v_and_b32_e32 v146, 15, v1
	s_lshl_b32 s48, s5, 10
	s_lshl_b32 s9, s8, 5
	v_lshlrev_b32_e32 v1, 4, v0
	s_add_u32 s58, s0, 0x9400000
	v_readlane_b32 s14, v255, 5
	v_add_u32_e32 v2, 0x2000, v1
	s_addc_u32 s59, s1, 0
	s_lshl_b32 s5, s14, 23
	v_ashrrev_i32_e32 v3, 31, v2
	s_add_u32 s5, s0, s5
	v_lshrrev_b32_e32 v3, 22, v3
	s_addc_u32 s7, s1, 0
	v_add_u32_e32 v3, v2, v3
	s_add_u32 s60, s5, 0x5400000
	v_ashrrev_i32_e32 v145, 10, v3
	v_readlane_b32 s5, v254, 32
	v_lshlrev_b32_e32 v144, 3, v147
	s_addc_u32 s61, s7, 0
	v_mul_i32_i24_e32 v3, 0x400, v145
	s_or_b32 s5, s5, s9
	v_lshl_or_b32 v148, s4, 6, v146
	v_sub_u32_e32 v10, v2, v3
	v_or_b32_e32 v2, s5, v144
	v_readlane_b32 s5, v254, 36
	v_lshrrev_b32_e32 v11, 4, v10
	v_ashrrev_i32_e32 v3, 31, v2
	v_add_u32_e32 v8, s5, v148
	v_ashrrev_i32_e32 v9, 31, v8
	v_lshlrev_b64 v[4:5], 11, v[8:9]
	v_bitop3_b32 v9, v11, v10, 32 bitop3:0x6c
	v_ashrrev_i32_e32 v10, 31, v9
	v_lshrrev_b32_e32 v10, 26, v10
	v_add_u32_e32 v10, v9, v10
	v_lshlrev_b32_e32 v11, 3, v145
	v_ashrrev_i32_e32 v153, 6, v10
	v_and_b32_e32 v11, -16, v11
	v_add_u32_e32 v11, v153, v11
	v_and_b32_e32 v12, 3, v153
	s_mov_b32 s5, 0x7ffe0
	v_lshl_add_u64 v[4:5], s[18:19], 0, v[4:5]
	v_lshlrev_b64 v[34:35], 1, v[2:3]
	v_and_or_b32 v16, v11, s5, v12
	v_lshrrev_b32_e32 v12, 2, v11
	v_and_b32_e32 v10, 0xc0, v10
	v_lshl_add_u64 v[2:3], v[4:5], 0, v[34:35]
	v_and_b32_e32 v17, 4, v12
	v_lshlrev_b32_e32 v12, 1, v11
	v_sub_u32_e32 v9, v9, v10
	global_load_dwordx4 v[4:7], v[2:3], off
	v_and_b32_e32 v18, 24, v12
	global_load_dwordx4 v[12:15], v[2:3], off offset:256
	v_lshlrev_b32_e32 v3, 5, v145
	v_ashrrev_i16_sdwa v9, v233, sext(v9) dst_sel:DWORD dst_unused:UNUSED_PAD src0_sel:DWORD src1_sel:BYTE_0
	v_and_b32_e32 v3, 32, v3
	v_bfe_i32 v154, v9, 0, 16
	v_or3_b32 v2, v16, v17, v18
	v_add_lshl_u32 v9, v3, v154, 1
	v_lshl_add_u32 v112, v2, 13, v9
	v_lshl_add_u32 v132, v11, 13, v9
	v_bfe_i32 v9, v0, 27, 1
	v_lshrrev_b32_e32 v9, 22, v9
	v_add_u32_e32 v9, v1, v9
	v_and_b32_e32 v9, 0xfffffc00, v9
	v_add_u32_e32 v2, 16, v8
	v_sub_u32_e32 v1, v1, v9
	v_ashrrev_i32_e32 v3, 31, v2
	v_lshrrev_b32_e32 v9, 4, v1
	v_lshlrev_b64 v[2:3], 11, v[2:3]
	v_bitop3_b32 v9, v9, v1, 32 bitop3:0x6c
	v_lshl_add_u64 v[2:3], s[18:19], 0, v[2:3]
	v_ashrrev_i32_e32 v1, 31, v9
	v_lshl_add_u64 v[2:3], v[2:3], 0, v[34:35]
	v_lshrrev_b32_e32 v1, 26, v1
	global_load_dwordx4 v[20:23], v[2:3], off
	global_load_dwordx4 v[28:31], v[2:3], off offset:256
	v_add_u32_e32 v2, v9, v1
	v_ashrrev_i32_e32 v1, 31, v0
	v_lshrrev_b32_e32 v1, 26, v1
	v_add_u32_e32 v0, v0, v1
	v_ashrrev_i32_e32 v156, 6, v0
	v_add_u32_e32 v0, 32, v8
	v_ashrrev_i32_e32 v1, 31, v0
	v_lshlrev_b64 v[0:1], 11, v[0:1]
	v_ashrrev_i32_e32 v155, 6, v2
	v_lshl_add_u64 v[0:1], s[18:19], 0, v[0:1]
	v_and_b32_e32 v2, 0xc0, v2
	v_lshl_add_u64 v[0:1], v[0:1], 0, v[34:35]
	v_sub_u32_e32 v2, v9, v2
	global_load_dwordx4 v[36:39], v[0:1], off
	global_load_dwordx4 v[44:47], v[0:1], off offset:256
	v_ashrrev_i16_sdwa v0, v233, sext(v2) dst_sel:DWORD dst_unused:UNUSED_PAD src0_sel:DWORD src1_sel:BYTE_0
	v_bfe_i32 v157, v0, 0, 16
	v_add_u32_e32 v0, 48, v8
	v_lshlrev_b32_e32 v3, 3, v156
	v_ashrrev_i32_e32 v1, 31, v0
	v_and_b32_e32 v3, -16, v3
	v_lshlrev_b64 v[0:1], 11, v[0:1]
	v_add_u32_e32 v3, v155, v3
	v_and_b32_e32 v10, 3, v155
	v_lshl_add_u64 v[0:1], s[18:19], 0, v[0:1]
	v_and_or_b32 v10, v3, s5, v10
	v_lshl_add_u64 v[8:9], v[0:1], 0, v[34:35]
	v_readlane_b32 s5, v254, 33
	global_load_dwordx4 v[52:55], v[8:9], off
	global_load_dwordx4 v[60:63], v[8:9], off offset:256
	v_add_u32_e32 v8, s5, v148
	v_ashrrev_i32_e32 v9, 31, v8
	v_lshrrev_b32_e32 v11, 2, v3
	v_lshlrev_b32_e32 v16, 1, v3
	v_lshlrev_b64 v[8:9], 11, v[8:9]
	v_and_b32_e32 v11, 4, v11
	v_and_b32_e32 v16, 24, v16
	v_lshl_add_u64 v[8:9], s[18:19], 0, v[8:9]
	v_or3_b32 v10, v10, v11, v16
	v_lshl_add_u64 v[16:17], v[8:9], 0, v[34:35]
	v_readlane_b32 s5, v254, 34
	global_load_dwordx4 v[68:71], v[16:17], off
	global_load_dwordx4 v[76:79], v[16:17], off offset:256
	v_add_u32_e32 v16, s5, v148
	v_readlane_b32 s5, v254, 35
	v_ashrrev_i32_e32 v17, 31, v16
	v_lshlrev_b64 v[16:17], 11, v[16:17]
	v_add_u32_e32 v26, s5, v148
	v_readlane_b32 s5, v254, 37
	v_ashrrev_i32_e32 v27, 31, v26
	v_lshlrev_b64 v[26:27], 11, v[26:27]
	v_add_u32_e32 v40, s5, v148
	v_ashrrev_i32_e32 v41, 31, v40
	v_lshlrev_b64 v[40:41], 11, v[40:41]
	v_lshl_add_u64 v[16:17], s[18:19], 0, v[16:17]
	v_lshl_add_u64 v[26:27], s[18:19], 0, v[26:27]
	v_lshl_add_u64 v[40:41], s[18:19], 0, v[40:41]
	v_lshl_add_u64 v[24:25], v[16:17], 0, v[34:35]
	v_lshl_add_u64 v[32:33], v[26:27], 0, v[34:35]
	v_lshl_add_u64 v[42:43], v[40:41], 0, v[34:35]
	global_load_dwordx4 v[84:87], v[24:25], off
	global_load_dwordx4 v[92:95], v[24:25], off offset:256
	global_load_dwordx4 v[100:103], v[32:33], off
	global_load_dwordx4 v[108:111], v[32:33], off offset:256
	global_load_dwordx4 v[120:123], v[42:43], off
	global_load_dwordx4 v[128:131], v[42:43], off offset:256
	v_readlane_b32 s15, v255, 6
	v_lshlrev_b32_e32 v11, 5, v156
	v_readlane_b32 s14, v254, 50
	v_and_b32_e32 v11, 32, v11
	v_readlane_b32 s15, v254, 51
	s_add_u32 s40, s60, s14
	v_add_lshl_u32 v2, v11, v157, 1
	s_addc_u32 s41, s61, s15
	s_add_i32 s62, s48, 0
	v_lshl_add_u32 v114, v10, 13, v2
	v_lshl_add_u32 v134, v3, 13, v2
	s_add_i32 m0, s62, 0x10000
	s_nop 0
	global_load_lds_dwordx4 v114, s[40:41]
	s_add_i32 m0, s62, 0x12000
	v_readlane_b32 s14, v254, 46
	v_readlane_b32 s15, v254, 47
	s_add_u32 s50, s58, s14
	s_addc_u32 s51, s59, s15
	s_add_u32 s14, s40, 0x100000
	global_load_lds_dwordx4 v112, s[40:41]
	s_addc_u32 s15, s41, 0
	s_add_i32 m0, s62, 0x14000
	s_add_i32 s63, s62, 0x2000
	global_load_lds_dwordx4 v114, s[14:15]
	s_add_i32 m0, s62, 0x16000
	v_mov_b32_e32 v113, v115
	global_load_lds_dwordx4 v112, s[14:15]
	s_mov_b32 m0, s62
	s_add_u32 s14, s50, 0x100000
	global_load_lds_dwordx4 v134, s[50:51]
	s_mov_b32 m0, s63
	s_addc_u32 s15, s51, 0
	s_add_i32 s64, s62, 0x4000
	global_load_lds_dwordx4 v132, s[50:51]
	s_mov_b32 m0, s64
	s_add_i32 s65, s62, 0x6000
	global_load_lds_dwordx4 v134, s[14:15]
	s_mov_b32 m0, s65
	v_mov_b32_e32 v135, v115
	global_load_lds_dwordx4 v132, s[14:15]
	s_waitcnt vmcnt(23)
; #define PG8_STAGE(bufoff, gbase, voff) do { _Pragma("unroll") for (int _i = 0; _i < 2; ++_i) \
;         __builtin_amdgcn_global_load_lds((const unsigned*)((const char*)(gbase) + (voff)[_i]), (PG8_LAS unsigned*)(lds + (bufoff) + ldsw + _i * 8192), 16, 0, 0); } while (0)
; #define PG8_BAR __builtin_amdgcn_s_barrier()
;     __device__ __forceinline__ void init(f32x4 (&acc)[2][2][4][2], const Unit& u, int wr, int wc, int fr, int fq) const {
;     ...
;                 for (int bj = 0; bj < 2; ++bj) { const size_t p = off + bj * HALF;
;                     if (base32) { acc[ai][bj][m][0] = *(const f32x4*)(base32 + p); acc[ai][bj][m][1] = *(const f32x4*)(base32 + p + 4); }
;                     else { const u32x4 r = *(const u32x4*)(xn + p); acc[ai][bj][m][0] = (f32x4){__uint_as_float(r.x << 16), __uint_as_float(r.x & 0xffff0000u), __uint_as_float(r.y << 16), __uint_as_float(r.y & 0xffff0000u)};
;                         acc[ai][bj][m][1] = (f32x4){__uint_as_float(r.z << 16), __uint_as_float(r.z & 0xffff0000u), __uint_as_float(r.w << 16), __uint_as_float(r.w & 0xffff0000u)}; } } }
; #pragma unroll
;         for (int ai = 0; ai < 2; ++ai)
; #pragma unroll
;             for (int bj = 0; bj < 2; ++bj)
; #pragma unroll
;                 for (int m = 0; m < 4; ++m) asm volatile("" : "+v"(acc[ai][bj][m][0]), "+v"(acc[ai][bj][m][1]));
; template <class Epi, class Sched, bool ALIGN_EPI = false, bool SP2 = false>
; __device__ __forceinline__ void gemm_phase(PG8_LAS unsigned char* lds, const Gemm g, const Sched& S, const Epi& E, const int tid_in) {
;     ...
;         PG8_STAGE(PG8_SB(0, 0), cB, voffB); PG8_STAGE(PG8_SB(0, 1), cB + hstepB, voffB); PG8_STAGE(PG8_SA(0, 0), cA, voffA); PG8_STAGE(PG8_SA(0, 1), cA + hstepA, voffA);
;         if (wr == 1) PG8_BAR;
	v_lshlrev_b32_e32 v0, 16, v4
	v_and_b32_e32 v1, 0xffff0000, v4
	v_lshlrev_b32_e32 v2, 16, v5
	v_and_b32_e32 v3, 0xffff0000, v5
	v_lshlrev_b32_e32 v4, 16, v6
	v_and_b32_e32 v5, 0xffff0000, v6
	v_lshlrev_b32_e32 v6, 16, v7
	v_and_b32_e32 v7, 0xffff0000, v7
	s_waitcnt vmcnt(22)
	v_lshlrev_b32_e32 v8, 16, v12
	v_and_b32_e32 v9, 0xffff0000, v12
	v_lshlrev_b32_e32 v10, 16, v13
	v_and_b32_e32 v11, 0xffff0000, v13
	v_lshlrev_b32_e32 v12, 16, v14
	v_and_b32_e32 v13, 0xffff0000, v14
	v_lshlrev_b32_e32 v14, 16, v15
	v_and_b32_e32 v15, 0xffff0000, v15
	s_waitcnt vmcnt(21)
	v_lshlrev_b32_e32 v16, 16, v20
	v_and_b32_e32 v17, 0xffff0000, v20
	v_lshlrev_b32_e32 v18, 16, v21
	v_and_b32_e32 v19, 0xffff0000, v21
	v_lshlrev_b32_e32 v20, 16, v22
	v_and_b32_e32 v21, 0xffff0000, v22
	v_lshlrev_b32_e32 v22, 16, v23
	v_and_b32_e32 v23, 0xffff0000, v23
	s_waitcnt vmcnt(20)
	v_lshlrev_b32_e32 v24, 16, v28
	v_and_b32_e32 v25, 0xffff0000, v28
	v_lshlrev_b32_e32 v26, 16, v29
	v_and_b32_e32 v27, 0xffff0000, v29
	v_lshlrev_b32_e32 v28, 16, v30
	v_and_b32_e32 v29, 0xffff0000, v30
	v_lshlrev_b32_e32 v30, 16, v31
	v_and_b32_e32 v31, 0xffff0000, v31
	s_waitcnt vmcnt(19)
	v_lshlrev_b32_e32 v32, 16, v36
	v_and_b32_e32 v33, 0xffff0000, v36
	v_lshlrev_b32_e32 v34, 16, v37
	v_and_b32_e32 v35, 0xffff0000, v37
	v_lshlrev_b32_e32 v36, 16, v38
	v_and_b32_e32 v37, 0xffff0000, v38
	v_lshlrev_b32_e32 v38, 16, v39
	v_and_b32_e32 v39, 0xffff0000, v39
	s_waitcnt vmcnt(18)
	v_lshlrev_b32_e32 v40, 16, v44
	v_and_b32_e32 v41, 0xffff0000, v44
	v_lshlrev_b32_e32 v42, 16, v45
	v_and_b32_e32 v43, 0xffff0000, v45
	v_lshlrev_b32_e32 v44, 16, v46
	v_and_b32_e32 v45, 0xffff0000, v46
	v_lshlrev_b32_e32 v46, 16, v47
	v_and_b32_e32 v47, 0xffff0000, v47
	s_waitcnt vmcnt(17)
	v_lshlrev_b32_e32 v48, 16, v52
	v_and_b32_e32 v49, 0xffff0000, v52
	v_lshlrev_b32_e32 v50, 16, v53
	v_and_b32_e32 v51, 0xffff0000, v53
	v_lshlrev_b32_e32 v52, 16, v54
	v_and_b32_e32 v53, 0xffff0000, v54
	v_lshlrev_b32_e32 v54, 16, v55
	v_and_b32_e32 v55, 0xffff0000, v55
	s_waitcnt vmcnt(16)
	v_lshlrev_b32_e32 v56, 16, v60
	v_and_b32_e32 v57, 0xffff0000, v60
	v_lshlrev_b32_e32 v58, 16, v61
	v_and_b32_e32 v59, 0xffff0000, v61
	v_lshlrev_b32_e32 v60, 16, v62
	v_and_b32_e32 v61, 0xffff0000, v62
	v_lshlrev_b32_e32 v62, 16, v63
	v_and_b32_e32 v63, 0xffff0000, v63
	s_waitcnt vmcnt(15)
	v_lshlrev_b32_e32 v64, 16, v68
	v_and_b32_e32 v65, 0xffff0000, v68
	v_lshlrev_b32_e32 v66, 16, v69
	v_and_b32_e32 v67, 0xffff0000, v69
	v_lshlrev_b32_e32 v68, 16, v70
	v_and_b32_e32 v69, 0xffff0000, v70
	v_lshlrev_b32_e32 v70, 16, v71
	v_and_b32_e32 v71, 0xffff0000, v71
	s_waitcnt vmcnt(14)
	v_lshlrev_b32_e32 v72, 16, v76
	v_and_b32_e32 v73, 0xffff0000, v76
	v_lshlrev_b32_e32 v74, 16, v77
	v_and_b32_e32 v75, 0xffff0000, v77
	v_lshlrev_b32_e32 v76, 16, v78
	v_and_b32_e32 v77, 0xffff0000, v78
	v_lshlrev_b32_e32 v78, 16, v79
	v_and_b32_e32 v79, 0xffff0000, v79
	s_waitcnt vmcnt(13)
	v_lshlrev_b32_e32 v80, 16, v84
	v_and_b32_e32 v81, 0xffff0000, v84
	v_lshlrev_b32_e32 v82, 16, v85
	v_and_b32_e32 v83, 0xffff0000, v85
	v_lshlrev_b32_e32 v84, 16, v86
	v_and_b32_e32 v85, 0xffff0000, v86
	v_lshlrev_b32_e32 v86, 16, v87
	v_and_b32_e32 v87, 0xffff0000, v87
	s_waitcnt vmcnt(12)
	v_lshlrev_b32_e32 v88, 16, v92
	v_and_b32_e32 v89, 0xffff0000, v92
	v_lshlrev_b32_e32 v90, 16, v93
	v_and_b32_e32 v91, 0xffff0000, v93
	v_lshlrev_b32_e32 v92, 16, v94
	v_and_b32_e32 v93, 0xffff0000, v94
	v_lshlrev_b32_e32 v94, 16, v95
	v_and_b32_e32 v95, 0xffff0000, v95
	s_waitcnt vmcnt(11)
	v_lshlrev_b32_e32 v96, 16, v100
	v_and_b32_e32 v97, 0xffff0000, v100
	v_lshlrev_b32_e32 v98, 16, v101
	v_and_b32_e32 v99, 0xffff0000, v101
	v_lshlrev_b32_e32 v100, 16, v102
	v_and_b32_e32 v101, 0xffff0000, v102
	v_lshlrev_b32_e32 v102, 16, v103
	v_and_b32_e32 v103, 0xffff0000, v103
	s_waitcnt vmcnt(10)
	v_lshlrev_b32_e32 v104, 16, v108
	v_and_b32_e32 v105, 0xffff0000, v108
	v_lshlrev_b32_e32 v106, 16, v109
	v_and_b32_e32 v107, 0xffff0000, v109
	v_lshlrev_b32_e32 v108, 16, v110
	v_and_b32_e32 v109, 0xffff0000, v110
	v_lshlrev_b32_e32 v110, 16, v111
	v_and_b32_e32 v111, 0xffff0000, v111
	s_waitcnt vmcnt(9)
	v_lshlrev_b32_e32 v116, 16, v120
	v_and_b32_e32 v117, 0xffff0000, v120
	v_lshlrev_b32_e32 v118, 16, v121
	v_and_b32_e32 v119, 0xffff0000, v121
	v_lshlrev_b32_e32 v120, 16, v122
	v_and_b32_e32 v121, 0xffff0000, v122
	v_lshlrev_b32_e32 v122, 16, v123
	v_and_b32_e32 v123, 0xffff0000, v123
	s_waitcnt vmcnt(8)
	v_lshlrev_b32_e32 v124, 16, v128
	v_and_b32_e32 v125, 0xffff0000, v128
	v_lshlrev_b32_e32 v126, 16, v129
	v_and_b32_e32 v127, 0xffff0000, v129
	v_lshlrev_b32_e32 v128, 16, v130
	v_and_b32_e32 v129, 0xffff0000, v130
	v_lshlrev_b32_e32 v130, 16, v131
	v_and_b32_e32 v131, 0xffff0000, v131
	v_mov_b32_e32 v133, v115
	s_cmp_eq_u32 s4, 1
	v_lshl_add_u64 v[142:143], s[40:41], 0, v[114:115]
	v_lshl_add_u64 v[140:141], s[40:41], 0, v[112:113]
	v_lshl_add_u64 v[136:137], s[50:51], 0, v[134:135]
	s_cselect_b64 s[20:21], -1, 0
	s_cmp_lg_u32 s4, 1
	v_lshl_add_u64 v[138:139], s[50:51], 0, v[132:133]
	s_cbranch_scc1 .LBB0_965
	s_barrier

; __device__ __forceinline__ void xcd_barrier(const XcdBarrier& b, const bool local_only = false) {
;     ...
;     }
;     __syncthreads();
; }
.Lxb_ld_exit_16:
.LBB0_1127:
	s_or_b64 exec, exec, s[8:9]
	s_waitcnt lgkmcnt(0)
	s_barrier
	s_mov_b64 s[12:13], s[94:95]
	s_cbranch_execnz .LBB0_833
	s_branch .LBB0_834
